# v17: dilated-attention flash loops get the per-lane rescale check (cross-half swap moved into the rare path), canonicalising max pairs and +0 add dropped; otherwise v16
# baseline (speedup 1.0000x reference)
; #define MFMA32(a, b, c) __builtin_amdgcn_mfma_f32_32x32x16_bf16((a), (b), (c), 0, 0, 0)
; __device__ __forceinline__ s16x4 vtr(ldsp p) { return __builtin_bit_cast(s16x4, __builtin_amdgcn_ds_read_tr16_b64_v4i16((LAS v4i16_t*)p)); }
; __device__ __forceinline__ bf16x8 cat8(s16x4 lo, s16x4 hi) { return (bf16x8){lo[0], lo[1], lo[2], lo[3], hi[0], hi[1], hi[2], hi[3]}; }
; template <int KS>
; __device__ __forceinline__ void flash_half(ldsp Kt, ldsp Vt, int kcol0, const bf16x8 (&qf)[KS], f32x16 (&o)[4], float& mc, float& l,
;                                            int key0, int qi, int qmin, int W, f32x16& negm, int lane) {
;     ...
;     float ps = 0.f;
; #pragma unroll
;     for (int r = 0; r < 16; ++r) { s0[r] = __builtin_amdgcn_exp2f(s0[r] - mc); ps += s0[r]; }
;     l += ps;
;     const int g = lane >> 4, i16 = lane & 15;
;     ldsp vb = Vt + (4 * (g >> 1) + (i16 >> 2)) * VP + (16 * (g & 1) + 4 * (i16 & 3)) * 2;
;     const bf16x8 p0 = pack8<0>(s0), p1 = pack8<1>(s0);
; #pragma unroll
;     for (int b = 0; b < 4; ++b) {
;         o[b] = MFMA32(cat8(vtr(vb + 64 * b), vtr(vb + 8 * VP + 64 * b)), p0, o[b]);
;         o[b] = MFMA32(cat8(vtr(vb + 16 * VP + 64 * b), vtr(vb + 24 * VP + 64 * b)), p1, o[b]); }
; __device__ __forceinline__ void dil_unit(const bf16* proj, bf16* dout, float* dlse, int g, int h, int dd, int rr, int ub, ldsp lds, int tid, int lane, int wave) {
;     ...
;         flash_tile<8>(lds, lds + T64, 0, qf, o, mc, l, 64 * t, qi, qmin, 128, negm, lane);
.LBB0_316:
	v_sub_f32_e32 v66, v66, v175
	v_exp_f32_e32 v66, v66
	v_sub_f32_e32 v67, v67, v175
	v_exp_f32_e32 v67, v67
	v_sub_f32_e32 v68, v68, v175
	v_exp_f32_e32 v68, v68
	v_sub_f32_e32 v69, v69, v175
	v_exp_f32_e32 v69, v69
	v_sub_f32_e32 v70, v70, v175
	v_exp_f32_e32 v177, v70
	v_add_f32_e32 v176, v67, v66
	v_add_f32_e32 v176, v68, v176
	v_add_f32_e32 v176, v69, v176
	v_sub_f32_e32 v71, v71, v175
	v_add_f32_e32 v70, v177, v176
	v_exp_f32_e32 v176, v71
	v_sub_f32_e32 v71, v72, v175
	v_exp_f32_e32 v178, v71
	v_sub_f32_e32 v71, v73, v175
	v_exp_f32_e32 v73, v71
	v_sub_f32_e32 v71, v74, v175
	v_exp_f32_e32 v74, v71
	v_sub_f32_e32 v71, v75, v175
	v_add_f32_e32 v70, v176, v70
	v_exp_f32_e32 v75, v71
	v_sub_f32_e32 v71, v76, v175
	v_add_f32_e32 v70, v178, v70
	v_exp_f32_e32 v76, v71
	v_sub_f32_e32 v71, v77, v175
	v_add_f32_e32 v70, v73, v70
	v_exp_f32_e32 v77, v71
	v_sub_f32_e32 v71, v78, v175
	v_add_f32_e32 v70, v74, v70
	v_exp_f32_e32 v78, v71
	v_sub_f32_e32 v71, v79, v175
	v_add_f32_e32 v70, v75, v70
	v_exp_f32_e32 v79, v71
	v_sub_f32_e32 v71, v80, v175
	v_add_f32_e32 v70, v76, v70
	v_exp_f32_e32 v80, v71
	v_sub_f32_e32 v71, v81, v175
	v_add_f32_e32 v70, v77, v70
	v_exp_f32_e32 v81, v71
	v_add_f32_e32 v70, v78, v70
	v_add_f32_e32 v70, v79, v70
	s_mulk_i32 s41, 0x2800
	v_add_f32_e32 v70, v80, v70
	v_add_f32_e32 v70, v81, v70
	v_add_u32_e32 v179, s41, v155
	v_add_f32_e32 v160, v160, v70
	v_cvt_pk_bf16_f32 v70, v66, v67
	v_cvt_pk_bf16_f32 v66, v74, v75
	v_cvt_pk_bf16_f32 v67, v76, v77
	ds_read_b64_tr_b16 v[74:75], v179 offset:17408
	ds_read_b64_tr_b16 v[76:77], v179 offset:19968
	v_cvt_pk_bf16_f32 v71, v68, v69
	v_cvt_pk_bf16_f32 v72, v177, v176
	v_cvt_pk_bf16_f32 v73, v178, v73
	v_cvt_pk_bf16_f32 v68, v78, v79
	v_cvt_pk_bf16_f32 v69, v80, v81
	s_waitcnt lgkmcnt(0)
	v_mfma_f32_32x32x16_bf16 v[50:65], v[74:77], v[70:73], v[50:65]
	ds_read_b64_tr_b16 v[74:75], v179 offset:22528
	ds_read_b64_tr_b16 v[76:77], v179 offset:25088
	s_waitcnt lgkmcnt(0)
	v_mfma_f32_32x32x16_bf16 v[50:65], v[74:77], v[66:69], v[50:65]
	ds_read_b64_tr_b16 v[74:75], v179 offset:17472
	ds_read_b64_tr_b16 v[76:77], v179 offset:20032
	s_waitcnt lgkmcnt(0)
	v_mfma_f32_32x32x16_bf16 v[34:49], v[74:77], v[70:73], v[34:49]
	ds_read_b64_tr_b16 v[74:75], v179 offset:22592
	ds_read_b64_tr_b16 v[76:77], v179 offset:25152
	s_waitcnt lgkmcnt(0)
	v_mfma_f32_32x32x16_bf16 v[34:49], v[74:77], v[66:69], v[34:49]
	ds_read_b64_tr_b16 v[74:75], v179 offset:17536
	ds_read_b64_tr_b16 v[76:77], v179 offset:20096
	s_waitcnt lgkmcnt(0)
	v_mfma_f32_32x32x16_bf16 v[18:33], v[74:77], v[70:73], v[18:33]
	ds_read_b64_tr_b16 v[74:75], v179 offset:22656
	ds_read_b64_tr_b16 v[76:77], v179 offset:25216
	s_waitcnt lgkmcnt(0)
	v_mfma_f32_32x32x16_bf16 v[18:33], v[74:77], v[66:69], v[18:33]
	ds_read_b64_tr_b16 v[74:75], v179 offset:17600
	ds_read_b64_tr_b16 v[76:77], v179 offset:20160
	s_waitcnt lgkmcnt(0)
	v_mfma_f32_32x32x16_bf16 v[2:17], v[74:77], v[70:73], v[2:17]
	ds_read_b64_tr_b16 v[70:71], v179 offset:22720
	ds_read_b64_tr_b16 v[72:73], v179 offset:25280
	s_waitcnt lgkmcnt(0)
	v_mfma_f32_32x32x16_bf16 v[2:17], v[70:73], v[66:69], v[2:17]

; __device__ __forceinline__ float xmax32(float v) { auto rr = __builtin_amdgcn_permlane32_swap(__float_as_uint(v), __float_as_uint(v), false, false); return fmaxf(__uint_as_float(rr[0]), __uint_as_float(rr[1])); }
; template <int KS>
; __device__ __forceinline__ void flash_half(ldsp Kt, ldsp Vt, int kcol0, const bf16x8 (&qf)[KS], f32x16 (&o)[4], float& mc, float& l,
;                                            int key0, int qi, int qmin, int W, f32x16& negm, int lane) {
;     ...
;     float m0 = fmaxf(s0[0], s0[1]), m1 = fmaxf(s0[2], s0[3]);
; #pragma unroll
;     for (int r = 4; r < 16; r += 4) { m0 = fmaxf(fmaxf(m0, s0[r]), s0[r + 1]); m1 = fmaxf(fmaxf(m1, s0[r + 2]), s0[r + 3]); }
;     float mx = fmaxf(m0, m1);
;     mx = xmax32(mx);
;     if (!__all(mx - mc <= 6.f)) {
;         const float mnew = fmaxf(mc, mx);
;         const float alpha = __builtin_amdgcn_exp2f(mc - mnew);
;         mc = mnew; l *= alpha;
; #pragma unroll
;         for (int b = 0; b < 4; ++b) o[b] *= alpha;
;     }
.LBB0_322:
	s_nop 10
	v_max_f32_e32 v176, v68, v69
	v_max3_f32 v177, v66, v67, v70
	v_max3_f32 v176, v176, v72, v73
	v_max3_f32 v177, v177, v71, v74
	v_max3_f32 v176, v176, v76, v77
	v_max3_f32 v177, v177, v75, v78
	v_max3_f32 v176, v176, v80, v81
	v_max3_f32 v176, v177, v79, v176
	v_sub_f32_e32 v177, v176, v175
	v_cmp_ge_f32_e32 vcc, s53, v177
	s_cmp_eq_u64 vcc, exec
	s_cbranch_scc1 .LBB0_316
	v_mov_b32_e32 v177, v176
	s_nop 1
	v_permlane32_swap_b32_e32 v176, v177
	v_max_f32_e32 v176, v176, v177
	v_max_f32_e32 v176, v176, v176
	v_max_f32_e32 v177, v175, v175
	v_max_f32_e32 v177, v177, v176
	v_sub_f32_e32 v175, v175, v177
	v_exp_f32_e32 v176, v175
	v_mov_b32_e32 v175, v177
	v_mul_f32_e32 v160, v160, v176
	v_pk_mul_f32 v[64:65], v[64:65], v[176:177] op_sel_hi:[1,0]
	v_pk_mul_f32 v[62:63], v[62:63], v[176:177] op_sel_hi:[1,0]
	v_pk_mul_f32 v[60:61], v[60:61], v[176:177] op_sel_hi:[1,0]
	v_pk_mul_f32 v[58:59], v[58:59], v[176:177] op_sel_hi:[1,0]
	v_pk_mul_f32 v[56:57], v[56:57], v[176:177] op_sel_hi:[1,0]
	v_pk_mul_f32 v[54:55], v[54:55], v[176:177] op_sel_hi:[1,0]
	v_pk_mul_f32 v[52:53], v[52:53], v[176:177] op_sel_hi:[1,0]
	v_pk_mul_f32 v[50:51], v[50:51], v[176:177] op_sel_hi:[1,0]
	v_pk_mul_f32 v[48:49], v[48:49], v[176:177] op_sel_hi:[1,0]
	v_pk_mul_f32 v[46:47], v[46:47], v[176:177] op_sel_hi:[1,0]
	v_pk_mul_f32 v[44:45], v[44:45], v[176:177] op_sel_hi:[1,0]
	v_pk_mul_f32 v[42:43], v[42:43], v[176:177] op_sel_hi:[1,0]
	v_pk_mul_f32 v[40:41], v[40:41], v[176:177] op_sel_hi:[1,0]
	v_pk_mul_f32 v[38:39], v[38:39], v[176:177] op_sel_hi:[1,0]
	v_pk_mul_f32 v[36:37], v[36:37], v[176:177] op_sel_hi:[1,0]
	v_pk_mul_f32 v[34:35], v[34:35], v[176:177] op_sel_hi:[1,0]
	v_pk_mul_f32 v[32:33], v[32:33], v[176:177] op_sel_hi:[1,0]
	v_pk_mul_f32 v[30:31], v[30:31], v[176:177] op_sel_hi:[1,0]
	v_pk_mul_f32 v[28:29], v[28:29], v[176:177] op_sel_hi:[1,0]
	v_pk_mul_f32 v[26:27], v[26:27], v[176:177] op_sel_hi:[1,0]
	v_pk_mul_f32 v[24:25], v[24:25], v[176:177] op_sel_hi:[1,0]
	v_pk_mul_f32 v[22:23], v[22:23], v[176:177] op_sel_hi:[1,0]
	v_pk_mul_f32 v[20:21], v[20:21], v[176:177] op_sel_hi:[1,0]
	v_pk_mul_f32 v[18:19], v[18:19], v[176:177] op_sel_hi:[1,0]
	v_pk_mul_f32 v[16:17], v[16:17], v[176:177] op_sel_hi:[1,0]
	v_pk_mul_f32 v[14:15], v[14:15], v[176:177] op_sel_hi:[1,0]
	v_pk_mul_f32 v[12:13], v[12:13], v[176:177] op_sel_hi:[1,0]
	v_pk_mul_f32 v[10:11], v[10:11], v[176:177] op_sel_hi:[1,0]
	v_pk_mul_f32 v[8:9], v[8:9], v[176:177] op_sel_hi:[1,0]
	v_pk_mul_f32 v[6:7], v[6:7], v[176:177] op_sel_hi:[1,0]
	v_pk_mul_f32 v[4:5], v[4:5], v[176:177] op_sel_hi:[1,0]
	v_pk_mul_f32 v[2:3], v[2:3], v[176:177] op_sel_hi:[1,0]
	s_branch .LBB0_316

; #define MFMA32(a, b, c) __builtin_amdgcn_mfma_f32_32x32x16_bf16((a), (b), (c), 0, 0, 0)
; __device__ __forceinline__ s16x4 vtr(ldsp p) { return __builtin_bit_cast(s16x4, __builtin_amdgcn_ds_read_tr16_b64_v4i16((LAS v4i16_t*)p)); }
; __device__ __forceinline__ bf16x8 cat8(s16x4 lo, s16x4 hi) { return (bf16x8){lo[0], lo[1], lo[2], lo[3], hi[0], hi[1], hi[2], hi[3]}; }
; template <int KS>
; __device__ __forceinline__ void flash_half(ldsp Kt, ldsp Vt, int kcol0, const bf16x8 (&qf)[KS], f32x16 (&o)[4], float& mc, float& l,
;                                            int key0, int qi, int qmin, int W, f32x16& negm, int lane) {
;     ...
;     float ps = 0.f;
; #pragma unroll
;     for (int r = 0; r < 16; ++r) { s0[r] = __builtin_amdgcn_exp2f(s0[r] - mc); ps += s0[r]; }
;     l += ps;
;     const int g = lane >> 4, i16 = lane & 15;
;     ldsp vb = Vt + (4 * (g >> 1) + (i16 >> 2)) * VP + (16 * (g & 1) + 4 * (i16 & 3)) * 2;
;     const bf16x8 p0 = pack8<0>(s0), p1 = pack8<1>(s0);
; #pragma unroll
;     for (int b = 0; b < 4; ++b) {
;         o[b] = MFMA32(cat8(vtr(vb + 64 * b), vtr(vb + 8 * VP + 64 * b)), p0, o[b]);
;         o[b] = MFMA32(cat8(vtr(vb + 16 * VP + 64 * b), vtr(vb + 24 * VP + 64 * b)), p1, o[b]); }
; __device__ __forceinline__ void dil_unit(const bf16* proj, bf16* dout, float* dlse, int g, int h, int dd, int rr, int ub, ldsp lds, int tid, int lane, int wave) {
;     ...
;         flash_tile<8>(lds + STG, lds + STG + T64, 0, qf, o, mc, l, 64 * (t + 1), qi, qmin, 128, negm, lane);
.LBB0_327:
	v_sub_f32_e32 v66, v66, v175
	v_exp_f32_e32 v66, v66
	v_sub_f32_e32 v67, v67, v175
	v_exp_f32_e32 v67, v67
	v_sub_f32_e32 v68, v68, v175
	v_exp_f32_e32 v68, v68
	v_sub_f32_e32 v69, v69, v175
	v_exp_f32_e32 v69, v69
	v_sub_f32_e32 v70, v70, v175
	v_exp_f32_e32 v177, v70
	v_add_f32_e32 v176, v67, v66
	v_add_f32_e32 v176, v68, v176
	v_add_f32_e32 v176, v69, v176
	v_sub_f32_e32 v71, v71, v175
	v_add_f32_e32 v70, v177, v176
	v_exp_f32_e32 v176, v71
	v_sub_f32_e32 v71, v72, v175
	v_exp_f32_e32 v178, v71
	v_sub_f32_e32 v71, v73, v175
	v_exp_f32_e32 v73, v71
	v_sub_f32_e32 v71, v74, v175
	v_exp_f32_e32 v74, v71
	v_sub_f32_e32 v71, v75, v175
	v_add_f32_e32 v70, v176, v70
	v_exp_f32_e32 v75, v71
	v_sub_f32_e32 v71, v76, v175
	v_add_f32_e32 v70, v178, v70
	v_exp_f32_e32 v76, v71
	v_sub_f32_e32 v71, v77, v175
	v_add_f32_e32 v70, v73, v70
	v_exp_f32_e32 v77, v71
	v_sub_f32_e32 v71, v78, v175
	v_add_f32_e32 v70, v74, v70
	v_exp_f32_e32 v78, v71
	v_sub_f32_e32 v71, v79, v175
	v_add_f32_e32 v70, v75, v70
	v_exp_f32_e32 v79, v71
	v_sub_f32_e32 v71, v80, v175
	v_add_f32_e32 v70, v76, v70
	v_exp_f32_e32 v80, v71
	v_sub_f32_e32 v71, v81, v175
	v_add_f32_e32 v70, v77, v70
	v_exp_f32_e32 v81, v71
	v_add_f32_e32 v70, v78, v70
	v_add_f32_e32 v70, v79, v70
	s_mulk_i32 s40, 0x2800
	v_add_f32_e32 v70, v80, v70
	v_add_f32_e32 v70, v81, v70
	v_add_u32_e32 v179, s40, v155
	v_add_f32_e32 v160, v160, v70
	v_cvt_pk_bf16_f32 v70, v66, v67
	v_cvt_pk_bf16_f32 v66, v74, v75
	v_cvt_pk_bf16_f32 v67, v76, v77
	ds_read_b64_tr_b16 v[74:75], v179 offset:55296
	ds_read_b64_tr_b16 v[76:77], v179 offset:57856
	v_cvt_pk_bf16_f32 v71, v68, v69
	v_cvt_pk_bf16_f32 v72, v177, v176
	v_cvt_pk_bf16_f32 v73, v178, v73
	v_cvt_pk_bf16_f32 v68, v78, v79
	v_cvt_pk_bf16_f32 v69, v80, v81
	s_waitcnt lgkmcnt(0)
	v_mfma_f32_32x32x16_bf16 v[50:65], v[74:77], v[70:73], v[50:65]
	ds_read_b64_tr_b16 v[74:75], v179 offset:60416
	ds_read_b64_tr_b16 v[76:77], v179 offset:62976
	s_waitcnt lgkmcnt(0)
	v_mfma_f32_32x32x16_bf16 v[50:65], v[74:77], v[66:69], v[50:65]
	ds_read_b64_tr_b16 v[74:75], v179 offset:55360
	ds_read_b64_tr_b16 v[76:77], v179 offset:57920
	s_waitcnt lgkmcnt(0)
	v_mfma_f32_32x32x16_bf16 v[34:49], v[74:77], v[70:73], v[34:49]
	ds_read_b64_tr_b16 v[74:75], v179 offset:60480
	ds_read_b64_tr_b16 v[76:77], v179 offset:63040
	s_waitcnt lgkmcnt(0)
	v_mfma_f32_32x32x16_bf16 v[34:49], v[74:77], v[66:69], v[34:49]
	ds_read_b64_tr_b16 v[74:75], v179 offset:55424
	ds_read_b64_tr_b16 v[76:77], v179 offset:57984
	s_waitcnt lgkmcnt(0)
	v_mfma_f32_32x32x16_bf16 v[18:33], v[74:77], v[70:73], v[18:33]
	ds_read_b64_tr_b16 v[74:75], v179 offset:60544
	ds_read_b64_tr_b16 v[76:77], v179 offset:63104
	s_waitcnt lgkmcnt(0)
	v_mfma_f32_32x32x16_bf16 v[18:33], v[74:77], v[66:69], v[18:33]
	ds_read_b64_tr_b16 v[74:75], v179 offset:55488
	ds_read_b64_tr_b16 v[76:77], v179 offset:58048
	s_waitcnt lgkmcnt(0)
	v_mfma_f32_32x32x16_bf16 v[2:17], v[74:77], v[70:73], v[2:17]
	ds_read_b64_tr_b16 v[70:71], v179 offset:60608
	ds_read_b64_tr_b16 v[72:73], v179 offset:63168
	s_waitcnt lgkmcnt(0)
	v_mfma_f32_32x32x16_bf16 v[2:17], v[70:73], v[66:69], v[2:17]
